# grid barriers after the two phases whose only global stores are write-through (attention, fix-up): L2 write-back instruction dropped at the XCD leader
# speedup vs baseline: 1.0048x; 1.0048x over previous
; __device__ __forceinline__ int lane_id() { int l; asm volatile("v_mbcnt_lo_u32_b32 %0, -1, 0\n\tv_mbcnt_hi_u32_b32 %0, -1, %0" : "=v"(l)); return l; }
; __device__ __forceinline__ unsigned xb_add(unsigned* p, unsigned v) { return __hip_atomic_fetch_add(p, v, __ATOMIC_RELAXED, __HIP_MEMORY_SCOPE_AGENT); }
; __device__ __forceinline__ XcdTok xcd_arrive(const XcdBarrier& b) {
;     XcdTok t; t.gen = 0u; t.tg = 0u; t.role = 0;
;     asm volatile("s_waitcnt vmcnt(0)" ::: "memory");
;     __syncthreads();
;     if (b.wave == 0 && lane_id() == 0) {
;         unsigned* bar = b.bar;
;         __builtin_amdgcn_s_waitcnt(0);
;         unsigned nloc = b.st[0], nx = b.st[1];
;         if (nloc == 0u) { xcd_barrier_complete(bar, b.x, nloc, nx); b.st[0] = nloc; b.st[1] = nx; }
;         const unsigned old = xb_add(&bar[XB_XSUB(b.x)], 1u);
;         t.gen = old / nloc;
;         if (old + 1u == (t.gen + 1u) * nloc) {
;             __builtin_amdgcn_fence(__ATOMIC_RELEASE, "agent");
;             asm volatile("s_waitcnt vmcnt(0)" ::: "memory");
;             const unsigned og = xb_add(&bar[XB_TOP], 1u);
;             t.tg = og / nx;
;             if (og + 1u == (t.tg + 1u) * nx) { xb_add(&bar[XB_TOPGEN], 1u); t.role = 2; } else t.role = 1;
.LBB0_560:
	s_or_b64 exec, exec, s[4:5]
	v_cvt_f32_u32_e32 v4, v1
	s_waitcnt vmcnt(1)
	v_readfirstlane_b32 s2, v3
	s_mov_b64 s[6:7], 0
	v_mov_b32_e32 v79, 0
	v_rcp_iflag_f32_e32 v4, v4
	v_add_u32_e32 v2, s2, v2
	v_add_u32_e32 v5, 1, v2
	s_mov_b64 s[16:17], 0
	v_mul_f32_e32 v3, 0x4f7ffffe, v4
	v_cvt_u32_f32_e32 v3, v3
	v_sub_u32_e32 v4, 0, v1
	v_mul_lo_u32 v4, v4, v3
	v_mul_hi_u32 v4, v3, v4
	v_add_u32_e32 v3, v3, v4
	v_mul_hi_u32 v3, v2, v3
	v_mul_lo_u32 v4, v3, v1
	v_sub_u32_e32 v2, v2, v4
	v_add_u32_e32 v6, 1, v3
	v_cmp_ge_u32_e32 vcc, v2, v1
	v_sub_u32_e32 v4, v2, v1
	s_nop 0
	v_cndmask_b32_e32 v3, v3, v6, vcc
	v_cndmask_b32_e32 v2, v2, v4, vcc
	v_add_u32_e32 v4, 1, v3
	v_cmp_ge_u32_e32 vcc, v2, v1
	s_nop 1
	v_cndmask_b32_e32 v75, v3, v4, vcc
	v_mul_lo_u32 v2, v1, v75
	v_add_u32_e32 v1, v2, v1
	v_cmp_eq_u32_e32 vcc, v5, v1
	s_and_saveexec_b64 s[4:5], vcc
	s_cbranch_execz .LBB0_568
	s_mov_b64 s[6:7], exec
	s_nop 0
	s_waitcnt lgkmcnt(0)
	s_waitcnt vmcnt(0)
	v_mbcnt_lo_u32_b32 v1, s6, 0
	v_mbcnt_hi_u32_b32 v1, s7, v1
	v_cmp_eq_u32_e32 vcc, 0, v1
	s_and_saveexec_b64 s[16:17], vcc
	s_cbranch_execz .LBB0_563
	s_bcnt1_i32_b64 s2, s[6:7]
	v_mov_b32_e32 v2, 0x7000
	v_mov_b32_e32 v3, s2
	global_atomic_add v2, v2, v3, s[10:11] offset:1024 sc0

; __device__ __forceinline__ unsigned xb_ld(unsigned* p)              { return __hip_atomic_load(p, __ATOMIC_RELAXED, __HIP_MEMORY_SCOPE_AGENT); }
; __device__ __forceinline__ unsigned xb_add(unsigned* p, unsigned v) { return __hip_atomic_fetch_add(p, v, __ATOMIC_RELAXED, __HIP_MEMORY_SCOPE_AGENT); }
; #define XB_SPIN(cond, bar) do { unsigned _sp = 0; while (cond) { __builtin_amdgcn_s_sleep(1); \
;     if ((++_sp & 255u) == 0u) { if (xb_ld(&(bar)[XB_TMO])) break; if (_sp > XB_SPIN_CAP) { atomicAdd(&(bar)[XB_TMO], 1u); break; } } } } while (0)
; __device__ __forceinline__ void xcd_barrier(const XcdBarrier& b) {
;     ...
;         const unsigned old = xb_add(&bar[XB_XSUB(b.x)], 1u);
;         const unsigned gen = old / nloc;
;         if (old + 1u == (gen + 1u) * nloc) {
;             __builtin_amdgcn_fence(__ATOMIC_RELEASE, "agent");
;             asm volatile("s_waitcnt vmcnt(0)" ::: "memory");
;             const unsigned og = xb_add(&bar[XB_TOP], 1u);
;             const unsigned tg = og / nx;
;             if (og + 1u == (tg + 1u) * nx) xb_add(&bar[XB_TOPGEN], 1u);
;             else XB_SPIN(xb_ld(&bar[XB_TOPGEN]) == tg, bar);
.LBB0_789:
	s_andn2_saveexec_b64 s[6:7], s[6:7]
	s_cbranch_execz .LBB0_809
	s_mov_b64 s[6:7], exec
	s_nop 0
	s_waitcnt lgkmcnt(0)
	s_waitcnt vmcnt(0)
	v_mbcnt_lo_u32_b32 v1, s6, 0
	v_mbcnt_hi_u32_b32 v1, s7, v1
	v_cmp_eq_u32_e32 vcc, 0, v1
	s_and_saveexec_b64 s[14:15], vcc
	s_cbranch_execz .LBB0_792
	s_bcnt1_i32_b64 s2, s[6:7]
	v_mov_b32_e32 v2, 0x7000
	v_mov_b32_e32 v3, s2
	global_atomic_add v2, v2, v3, s[10:11] offset:1024 sc0
